# weight conversion of layer l+1 moved into the grid seams of layer l (waves 1-7), P0 converts layer 0 only
# speedup vs baseline: 1.0084x; 1.0084x over previous
; #define LAS __attribute__((address_space(3)))
; __global__ void __launch_bounds__(NWAVES * 64, 2) hybrid_fwd(Args args) {
;     extern __shared__ __attribute__((aligned(16))) unsigned char lds[];
;     cg::grid_group grid = cg::this_grid();
;     const int tid = threadIdx.x, lane = tid & 63, wave = __builtin_amdgcn_readfirstlane(tid >> 6);
;     const int G = gridDim.x, bx = blockIdx.x;
;     const int vcu = (G % 8 == 0) ? (bx % 8) * (G / 8) + bx / 8 : bx;
;     const int lo = args.ph_lo, hi = args.ph_hi;
;     if (tid < 16) ((volatile LAS unsigned*)((LAS unsigned char*)lds + LDS_BARST))[tid] = 0u;
;     __syncthreads();
;     const XcdBarrier xbar = xcd_barrier_post((unsigned*)args.in[17], (volatile LAS unsigned*)((LAS unsigned char*)lds + LDS_BARST));
_Z10hybrid_fwd4Args:
	s_mov_b32 s98, 8
	s_mov_b32 s99, 0x3000
	s_mov_b32 s100, 0
	s_mov_b32 s101, 0
	s_load_dwordx2 s[88:89], s[0:1], 0x98
	s_mov_b64 s[84:85], s[0:1]
	s_add_u32 s20, s84, 0x98
	s_mov_b32 s80, s2
	s_addc_u32 s21, s85, 0
	v_and_b32_e32 v169, 0x3ff, v0
	s_waitcnt lgkmcnt(0)
	s_and_b32 s0, s88, 7
	v_readfirstlane_b32 s3, v169
	s_cmp_lg_u32 s0, 0
	v_writelane_b32 v254, s80, 0
	s_cbranch_scc1 .LBB0_2
	s_ashr_i32 s1, s80, 31
	s_lshr_b32 s1, s1, 29
	s_add_i32 s1, s80, s1
	s_and_b32 s2, s1, -8
	s_ashr_i32 s0, s88, 3
	s_sub_i32 s2, s80, s2
	s_mul_i32 s0, s0, s2
	s_ashr_i32 s1, s1, 3
	s_add_i32 s0, s0, s1
	v_writelane_b32 v254, s0, 0

; __global__ void __launch_bounds__(NWAVES * 64, 2) hybrid_fwd(Args args) {
;     ...
;         const int gw = vcu * NWAVES + wave, NGW = G * NWAVES;
;         constexpr int I_IN = (D / 64) * (PW / 64), I_OUT = (D / 64) * (D / 64), I_UP = (D / 64) * (FF / 64), I_DN = (FF / 64) * (D / 64), I_L = I_IN + I_OUT + I_UP + I_DN;
;         const float* const w_in = args.in[z + 1]; const float* const w_out = args.in[z + 2]; const float* const w_up = args.in[z + 13]; const float* const w_dn = args.in[z + 14];
;         const float* const g_attn = args.in[z + 11]; const float* const g_mlp = args.in[z + 12];
;         auto decode = [&](int it) -> TItem {
;             const int l = it / I_L; int r = it % I_L; TItem d;
;             const float* W; bf16* WT; const float* g = nullptr; int K = D, N = D, perm = 0;
;             if (r < I_IN) { W = w_in + (size_t)l * D * PW; WT = (bf16*)(ws + WS_WIN) + (size_t)l * PW * D; N = PW; g = g_attn + l * D; perm = 1; }
;             else if ((r -= I_IN) < I_OUT) { W = w_out + (size_t)l * D * D; WT = (bf16*)(ws + WS_WOUT) + (size_t)l * D * D; }
;             else if ((r -= I_OUT) < I_UP) { W = w_up + (size_t)l * D * FF; WT = (bf16*)(ws + WS_WUP) + (size_t)l * FF * D; N = FF; g = g_mlp + l * D; }
;             else { r -= I_UP; W = w_dn + (size_t)l * FF * D; WT = (bf16*)(ws + WS_WDN) + (size_t)l * D * FF; K = FF; }
;             const int nblk = N / 64, k0 = 64 * (r / nblk), n0 = 64 * (r % nblk);
;             d.src = W + (size_t)k0 * N + n0; d.g = g ? g + k0 : nullptr; d.dst = WT + (size_t)(k0 >> 6) * (256 * 64); d.N = N; d.K = K; d.perm = perm | (n0 << 1);
;             return d; };
;         {
;             int it = gw; f32x4 va[16]; float ga[16]; TItem d0;
;             if (it < DEPTH * I_L) { d0 = decode(it); titem_load(d0, va, ga, lane); }
;             while (it < DEPTH * I_L) {
;                 const int itn = it + NGW; f32x4 vb[16]; float gb[16]; TItem d1;
;                 if (itn < DEPTH * I_L) { d1 = decode(itn); titem_load(d1, vb, gb, lane); }
.Lcv_entry:
	s_load_dwordx2 s[4:5], s[84:85], 0x90
	v_and_b32_e32 v177, 63, v169
	s_waitcnt lgkmcnt(0)
	s_cmp_lt_i32 s4, 1
	s_cselect_b64 s[0:1], -1, 0
	s_cmp_gt_i32 s5, 0
	s_cselect_b64 s[4:5], -1, 0
	s_and_b64 s[0:1], s[0:1], s[4:5]
	s_andn2_b64 vcc, exec, s[0:1]
	s_cbranch_vccnz .LBB0_154
	v_readlane_b32 s1, v254, 0
	s_lshr_b32 s0, s3, 6
	s_mul_i32 s1, s1, s98
	s_add_i32 s22, s1, s0
	s_add_i32 s22, s22, s100
	s_cmp_lt_i32 s22, s99
	s_mov_b32 s0, 0
	s_cselect_b64 s[26:27], -1, 0
	s_ashr_i32 s1, s0, 31
	s_lshl_b64 s[0:1], s[0:1], 3
	s_add_u32 s6, s84, s0
	s_addc_u32 s7, s85, s1
	s_load_dwordx2 s[24:25], s[6:7], 0x88
	s_load_dwordx4 s[16:19], s[6:7], 0x8
	s_load_dwordx8 s[8:15], s[6:7], 0x58
	v_bfe_u32 v2, v169, 1, 5
	v_and_b32_e32 v144, 24, v2
	v_lshlrev_b32_e32 v1, 2, v169
	v_or_b32_e32 v145, 1, v144
	v_or_b32_e32 v146, 2, v144
	v_or_b32_e32 v147, 3, v144
	v_or_b32_e32 v148, 4, v144
	v_or_b32_e32 v149, 5, v144
	v_or_b32_e32 v150, 6, v144
	v_or_b32_e32 v151, 32, v144
	v_or_b32_e32 v152, 33, v144
	v_or_b32_e32 v153, 34, v144
	v_or_b32_e32 v154, 35, v144
	v_or_b32_e32 v155, 36, v144
	v_or_b32_e32 v156, 37, v144
	v_or_b32_e32 v157, 38, v144
	v_and_b32_e32 v158, 60, v1
	v_mov_b32_e32 v176, 0
	v_or_b32_e32 v159, 7, v2
	s_cmp_ge_i32 s22, s99
	v_or_b32_e32 v160, 39, v2
	s_cbranch_scc1 .LBB0_13
	s_mul_hi_i32 s0, s22, 0x2aaaaaab
	s_lshr_b32 s1, s0, 31
	s_ashr_i32 s0, s0, 11
	s_add_i32 s30, s0, s1
	s_mul_i32 s0, s30, 0x3000
	s_lshl_b32 s28, s30, 11
	s_sub_i32 s42, s22, s0
	s_ashr_i32 s31, s30, 31
	s_ashr_i32 s29, s28, 31
	s_cmpk_gt_i32 s42, 0xbff
	s_cbranch_scc0 .LBB0_14
	v_mov_b32_e32 v2, 0x1000
	v_sub_co_u32_e32 v2, vcc, s42, v2
	s_andn2_b64 vcc, exec, vcc
	v_readfirstlane_b32 s43, v2
	s_cbranch_vccz .LBB0_15
	v_mov_b32_e32 v2, 0x2000
	v_sub_co_u32_e32 v2, vcc, s42, v2
	s_movk_i32 s3, 0x2000
	v_readfirstlane_b32 s23, v2
	s_lshl_b64 s[38:39], s[30:31], 26
	s_andn2_b64 vcc, exec, vcc
	s_lshl_b64 s[40:41], s[30:31], 25
	s_cbranch_vccz .LBB0_16
	s_waitcnt lgkmcnt(0)
	s_add_u32 s4, s14, s38
	s_addc_u32 s5, s15, s39
	s_add_u32 s0, s24, s40
	s_addc_u32 s1, s25, s41
	s_add_u32 s0, s0, 0x10200000
	s_addc_u32 s1, s1, 0
	s_mov_b64 s[36:37], 0
	s_mov_b32 s43, s23
	s_branch .LBB0_17
.LBB0_13:
	v_mov_b32_e32 v178, 0
	v_mov_b32_e32 v174, 0
	v_mov_b32_e32 v175, 0
	v_mov_b32_e32 v172, 0
	v_mov_b32_e32 v173, 0
	v_mov_b32_e32 v170, 0
	v_mov_b32_e32 v171, 0
	v_mov_b32_e32 v167, 0
	v_mov_b32_e32 v168, 0
	v_mov_b32_e32 v165, 0
	v_mov_b32_e32 v166, 0
	v_mov_b32_e32 v163, 0
	v_mov_b32_e32 v164, 0
	v_mov_b32_e32 v161, 0
	v_mov_b32_e32 v162, 0
	s_andn2_b64 vcc, exec, s[26:27]
	s_mul_i32 s26, s88, s98
	s_cbranch_vccz .LBB0_56
	s_branch .LBB0_130

; __global__ void __launch_bounds__(NWAVES * 64, 2) hybrid_fwd(Args args) {
;     ...
;             d.src = W + (size_t)k0 * N + n0; d.g = g ? g + k0 : nullptr; d.dst = WT + (size_t)(k0 >> 6) * (256 * 64); d.N = N; d.K = K; d.perm = perm | (n0 << 1);
;             return d; };
;         {
;             int it = gw; f32x4 va[16]; float ga[16]; TItem d0;
;             if (it < DEPTH * I_L) { d0 = decode(it); titem_load(d0, va, ga, lane); }
;             while (it < DEPTH * I_L) {
;                 const int itn = it + NGW; f32x4 vb[16]; float gb[16]; TItem d1;
;                 if (itn < DEPTH * I_L) { d1 = decode(itn); titem_load(d1, vb, gb, lane); }
.LBB0_55:
	s_ashr_i32 s29, s28, 31
	s_lshl_b64 s[4:5], s[28:29], 15
	s_add_u32 s0, s0, s4
	s_addc_u32 s1, s1, s5
	s_lshl_b32 s4, s40, 7
	s_or_b32 s23, s4, s33
	s_andn2_b64 vcc, exec, s[26:27]
	s_mul_i32 s26, s88, s98
	s_cbranch_vccnz .LBB0_130

; __global__ void __launch_bounds__(NWAVES * 64, 2) hybrid_fwd(Args args) {
;     ...
;         auto decode = [&](int it) -> TItem {
;             const int l = it / I_L; int r = it % I_L; TItem d;
;             const float* W; bf16* WT; const float* g = nullptr; int K = D, N = D, perm = 0;
;             if (r < I_IN) { W = w_in + (size_t)l * D * PW; WT = (bf16*)(ws + WS_WIN) + (size_t)l * PW * D; N = PW; g = g_attn + l * D; perm = 1; }
;             else if ((r -= I_IN) < I_OUT) { W = w_out + (size_t)l * D * D; WT = (bf16*)(ws + WS_WOUT) + (size_t)l * D * D; }
;             else if ((r -= I_OUT) < I_UP) { W = w_up + (size_t)l * D * FF; WT = (bf16*)(ws + WS_WUP) + (size_t)l * FF * D; N = FF; g = g_mlp + l * D; }
;             else { r -= I_UP; W = w_dn + (size_t)l * FF * D; WT = (bf16*)(ws + WS_WDN) + (size_t)l * D * FF; K = FF; }
;             const int nblk = N / 64, k0 = 64 * (r / nblk), n0 = 64 * (r % nblk);
;             d.src = W + (size_t)k0 * N + n0; d.g = g ? g + k0 : nullptr; d.dst = WT + (size_t)(k0 >> 6) * (256 * 64); d.N = N; d.K = K; d.perm = perm | (n0 << 1);
;             return d; };
;         {
;             int it = gw; f32x4 va[16]; float ga[16]; TItem d0;
;             if (it < DEPTH * I_L) { d0 = decode(it); titem_load(d0, va, ga, lane); }
;             while (it < DEPTH * I_L) {
;                 const int itn = it + NGW; f32x4 vb[16]; float gb[16]; TItem d1;
;                 if (itn < DEPTH * I_L) { d1 = decode(itn); titem_load(d1, vb, gb, lane); }
.LBB0_58:
	s_add_i32 s57, s57, s26
	s_cmp_lt_i32 s57, s99
	s_cselect_b64 s[30:31], -1, 0
	s_cmp_ge_i32 s57, s99
	s_cselect_b64 s[28:29], -1, 0
	s_and_b64 vcc, exec, s[28:29]
	s_cbranch_vccnz .LBB0_95
	s_mul_hi_i32 s4, s57, 0x2aaaaaab
	s_lshr_b32 s5, s4, 31
	s_ashr_i32 s4, s4, 11
	s_add_i32 s36, s4, s5
	s_mul_i32 s4, s36, 0xffffd000
	s_add_i32 s44, s57, s4
	s_cmpk_gt_i32 s44, 0xbff
	s_mov_b64 s[38:39], -1
	s_cbranch_scc0 .LBB0_68
	s_mul_i32 s4, s36, 0x3000
	s_sub_i32 s60, s57, s4
	s_ashr_i32 s37, s36, 31
	s_cmpk_gt_u32 s44, 0xfff
	s_cbranch_scc0 .LBB0_65
	s_lshl_b64 s[42:43], s[36:37], 26
	s_lshl_b64 s[40:41], s[36:37], 25
	s_cmpk_gt_u32 s44, 0x1fff
	s_cbranch_scc0 .LBB0_63
	s_add_i32 s45, s60, 0xffffe000
	s_add_u32 s4, s14, s42
	s_addc_u32 s5, s15, s43
	s_add_u32 s34, s27, s40
	s_addc_u32 s35, s33, s41
	s_mov_b64 s[38:39], 0

; __global__ void __launch_bounds__(NWAVES * 64, 2) hybrid_fwd(Args args) {
;     ...
;             }
;         }
;         const int gt = bx * (NWAVES * 64) + tid, NGT = G * NWAVES * 64;
;         for (int i = gt; i < 16 * 384; i += NGT) { const int hm = i / 384, d = i % 384 - 128;
;             BT[i] = d < 0 ? -1e30f : args.in[z + 15][t5_bucket(d > 127 ? 127 : d) * 16 + hm] * 1.4426950408889634f; }
.LBB0_130:
	s_cmp_lg_u32 s101, 0
	s_cbranch_scc1 .Lcv_restore
	s_waitcnt vmcnt(15)
	v_lshl_add_u32 v2, s80, 9, v169
	s_movk_i32 s0, 0x1800
	v_cmp_gt_i32_e32 vcc, s0, v2
	s_and_saveexec_b64 s[0:1], vcc
	s_cbranch_execz .LBB0_137
	s_waitcnt lgkmcnt(0)
	s_add_u32 s4, s24, 0x80000
	s_addc_u32 s5, s25, 0
	s_lshl_b32 s3, s88, 9
	s_mov_b64 s[8:9], 0
	s_mov_b32 s14, 0x2aaaaaab
	s_movk_i32 s15, 0x7f
	s_movk_i32 s16, 0x42
	s_movk_i32 s17, 0x4c
	s_movk_i32 s18, 0x56
	s_movk_i32 s19, 0x62
	s_movk_i32 s23, 0x70
	s_movk_i32 s27, 0x17ff
	s_branch .LBB0_134

; __device__ __forceinline__ unsigned xb_ld(unsigned* p)              { return __hip_atomic_load(p, __ATOMIC_RELAXED, __HIP_MEMORY_SCOPE_AGENT); }
; __device__ __forceinline__ unsigned xb_add(unsigned* p, unsigned v) { return __hip_atomic_fetch_add(p, v, __ATOMIC_RELAXED, __HIP_MEMORY_SCOPE_AGENT); }
; #define XB_SPIN(cond, bar) do { unsigned _sp = 0; while (cond) { __builtin_amdgcn_s_sleep(1); \
;     if ((++_sp & 255u) == 0u) { if (xb_ld(&(bar)[XB_TMO])) break; if (_sp > XB_SPIN_CAP) { atomicAdd(&(bar)[XB_TMO], 1u); break; } } } } while (0)
; __device__ __forceinline__ void xcd_barrier(const XcdBarrier& b) {
;     asm volatile("s_waitcnt vmcnt(0)" ::: "memory");
;     __syncthreads();
;     if (threadIdx.x == 0) {
;         unsigned* bar = b.bar;
;         __builtin_amdgcn_s_waitcnt(0);
;         unsigned nloc = b.st[0], nx = b.st[1];
;         if (nloc == 0u) { xcd_barrier_complete(bar, b.x, nloc, nx); b.st[0] = nloc; b.st[1] = nx; }
;         const unsigned old = xb_add(&bar[XB_XSUB(b.x)], 1u);
;         const unsigned gen = old / nloc;
;         if (old + 1u == (gen + 1u) * nloc) {
;             __builtin_amdgcn_fence(__ATOMIC_RELEASE, "agent");
;             asm volatile("s_waitcnt vmcnt(0)" ::: "memory");
;             const unsigned og = xb_add(&bar[XB_TOP], 1u);
;             const unsigned tg = og / nx;
;             if (og + 1u == (tg + 1u) * nx) xb_add(&bar[XB_TOPGEN], 1u);
;             else XB_SPIN(xb_ld(&bar[XB_TOPGEN]) == tg, bar);
;             __builtin_amdgcn_fence(__ATOMIC_ACQUIRE, "agent");
;             xb_add(&bar[XB_XGEN(b.x)], 1u);
;             asm volatile("s_waitcnt vmcnt(0)" ::: "memory");
;         } else {
;             XB_SPIN(xb_ld(&bar[XB_XGEN(b.x)]) == gen, bar);
;             __builtin_amdgcn_fence(__ATOMIC_ACQUIRE, "agent");
;             asm volatile("s_waitcnt vmcnt(0)" ::: "memory");
;         }
;     }
;     __syncthreads();
; }
.LBB0_156:
	s_or_b64 exec, exec, s[0:1]
	v_readfirstlane_b32 s101, v169
	s_nop 3
	s_lshr_b32 s101, s101, 6
	s_cmp_eq_u32 s101, 0
	s_cbranch_scc1 .Lcv_skip_E
	v_readlane_b32 s100, v255, 44
	s_nop 3
	s_cmp_gt_u32 s100, 2
	s_cbranch_scc1 .Lcv_skip_E
	s_add_i32 s100, s100, 1
	s_mul_i32 s98, s100, 0x3000
	s_add_i32 s100, s98, 9832
	s_add_i32 s99, s100, 2458
	s_add_i32 s98, s98, 0x3000
	s_min_i32 s99, s99, s98
	s_sub_i32 s100, s100, 1
	s_mov_b32 s98, 7
	s_mov_b32 s101, 5
	v_readfirstlane_b32 s3, v169
	s_branch .Lcv_entry
.Lcv_skip_E:
	s_mov_b32 s101, 0
.Lcv_ret_E:
	s_waitcnt lgkmcnt(0)
	s_barrier

; __device__ __forceinline__ unsigned xb_ld(unsigned* p)              { return __hip_atomic_load(p, __ATOMIC_RELAXED, __HIP_MEMORY_SCOPE_AGENT); }
; __device__ __forceinline__ unsigned xb_add(unsigned* p, unsigned v) { return __hip_atomic_fetch_add(p, v, __ATOMIC_RELAXED, __HIP_MEMORY_SCOPE_AGENT); }
; #define XB_SPIN(cond, bar) do { unsigned _sp = 0; while (cond) { __builtin_amdgcn_s_sleep(1); \
;     if ((++_sp & 255u) == 0u) { if (xb_ld(&(bar)[XB_TMO])) break; if (_sp > XB_SPIN_CAP) { atomicAdd(&(bar)[XB_TMO], 1u); break; } } } } while (0)
; __device__ __forceinline__ void xcd_barrier(const XcdBarrier& b) {
;     asm volatile("s_waitcnt vmcnt(0)" ::: "memory");
;     __syncthreads();
;     if (threadIdx.x == 0) {
;         unsigned* bar = b.bar;
;         __builtin_amdgcn_s_waitcnt(0);
;         unsigned nloc = b.st[0], nx = b.st[1];
;         if (nloc == 0u) { xcd_barrier_complete(bar, b.x, nloc, nx); b.st[0] = nloc; b.st[1] = nx; }
;         const unsigned old = xb_add(&bar[XB_XSUB(b.x)], 1u);
;         const unsigned gen = old / nloc;
;         if (old + 1u == (gen + 1u) * nloc) {
;             __builtin_amdgcn_fence(__ATOMIC_RELEASE, "agent");
;             asm volatile("s_waitcnt vmcnt(0)" ::: "memory");
;             const unsigned og = xb_add(&bar[XB_TOP], 1u);
;             const unsigned tg = og / nx;
;             if (og + 1u == (tg + 1u) * nx) xb_add(&bar[XB_TOPGEN], 1u);
;             else XB_SPIN(xb_ld(&bar[XB_TOPGEN]) == tg, bar);
;             __builtin_amdgcn_fence(__ATOMIC_ACQUIRE, "agent");
;             xb_add(&bar[XB_XGEN(b.x)], 1u);
;             asm volatile("s_waitcnt vmcnt(0)" ::: "memory");
;         } else {
;             XB_SPIN(xb_ld(&bar[XB_XGEN(b.x)]) == gen, bar);
;             __builtin_amdgcn_fence(__ATOMIC_ACQUIRE, "agent");
;             asm volatile("s_waitcnt vmcnt(0)" ::: "memory");
;         }
;     }
;     __syncthreads();
; }
.LBB0_292:
	s_or_b64 exec, exec, s[0:1]
	v_readfirstlane_b32 s101, v169
	s_nop 3
	s_lshr_b32 s101, s101, 6
	s_cmp_eq_u32 s101, 0
	s_cbranch_scc1 .Lcv_skip_A
	v_readlane_b32 s100, v255, 44
	s_nop 3
	s_cmp_gt_u32 s100, 2
	s_cbranch_scc1 .Lcv_skip_A
	s_add_i32 s100, s100, 1
	s_mul_i32 s98, s100, 0x3000
	s_add_i32 s100, s98, 0
	s_add_i32 s99, s100, 2458
	s_add_i32 s98, s98, 0x3000
	s_min_i32 s99, s99, s98
	s_sub_i32 s100, s100, 1
	s_mov_b32 s98, 7
	s_mov_b32 s101, 1
	v_readfirstlane_b32 s3, v169
	s_branch .Lcv_entry

; __device__ __forceinline__ unsigned xb_ld(unsigned* p)              { return __hip_atomic_load(p, __ATOMIC_RELAXED, __HIP_MEMORY_SCOPE_AGENT); }
; __device__ __forceinline__ unsigned xb_add(unsigned* p, unsigned v) { return __hip_atomic_fetch_add(p, v, __ATOMIC_RELAXED, __HIP_MEMORY_SCOPE_AGENT); }
; #define XB_SPIN(cond, bar) do { unsigned _sp = 0; while (cond) { __builtin_amdgcn_s_sleep(1); \
;     if ((++_sp & 255u) == 0u) { if (xb_ld(&(bar)[XB_TMO])) break; if (_sp > XB_SPIN_CAP) { atomicAdd(&(bar)[XB_TMO], 1u); break; } } } } while (0)
; __device__ __forceinline__ void xcd_barrier(const XcdBarrier& b) {
;     asm volatile("s_waitcnt vmcnt(0)" ::: "memory");
;     __syncthreads();
;     if (threadIdx.x == 0) {
;         unsigned* bar = b.bar;
;         __builtin_amdgcn_s_waitcnt(0);
;         unsigned nloc = b.st[0], nx = b.st[1];
;         if (nloc == 0u) { xcd_barrier_complete(bar, b.x, nloc, nx); b.st[0] = nloc; b.st[1] = nx; }
;         const unsigned old = xb_add(&bar[XB_XSUB(b.x)], 1u);
;         const unsigned gen = old / nloc;
;         if (old + 1u == (gen + 1u) * nloc) {
;             __builtin_amdgcn_fence(__ATOMIC_RELEASE, "agent");
;             asm volatile("s_waitcnt vmcnt(0)" ::: "memory");
;             const unsigned og = xb_add(&bar[XB_TOP], 1u);
;             const unsigned tg = og / nx;
;             if (og + 1u == (tg + 1u) * nx) xb_add(&bar[XB_TOPGEN], 1u);
;             else XB_SPIN(xb_ld(&bar[XB_TOPGEN]) == tg, bar);
;             __builtin_amdgcn_fence(__ATOMIC_ACQUIRE, "agent");
;             xb_add(&bar[XB_XGEN(b.x)], 1u);
;             asm volatile("s_waitcnt vmcnt(0)" ::: "memory");
;         } else {
;             XB_SPIN(xb_ld(&bar[XB_XGEN(b.x)]) == gen, bar);
;             __builtin_amdgcn_fence(__ATOMIC_ACQUIRE, "agent");
;             asm volatile("s_waitcnt vmcnt(0)" ::: "memory");
;         }
;     }
;     __syncthreads();
; }
.LBB0_435:
	s_or_b64 exec, exec, s[0:1]
	v_readfirstlane_b32 s101, v169
	s_nop 3
	s_lshr_b32 s101, s101, 6
	s_cmp_eq_u32 s101, 0
	s_cbranch_scc1 .Lcv_skip_B
	v_readlane_b32 s100, v255, 44
	s_nop 3
	s_cmp_gt_u32 s100, 2
	s_cbranch_scc1 .Lcv_skip_B
	s_add_i32 s100, s100, 1
	s_mul_i32 s98, s100, 0x3000
	s_add_i32 s100, s98, 2458
	s_add_i32 s99, s100, 2458
	s_add_i32 s98, s98, 0x3000
	s_min_i32 s99, s99, s98
	s_sub_i32 s100, s100, 1
	s_mov_b32 s98, 7
	s_mov_b32 s101, 2
	v_readfirstlane_b32 s3, v169
	s_branch .Lcv_entry

; __device__ __forceinline__ unsigned xb_ld(unsigned* p)              { return __hip_atomic_load(p, __ATOMIC_RELAXED, __HIP_MEMORY_SCOPE_AGENT); }
; __device__ __forceinline__ unsigned xb_add(unsigned* p, unsigned v) { return __hip_atomic_fetch_add(p, v, __ATOMIC_RELAXED, __HIP_MEMORY_SCOPE_AGENT); }
; #define XB_SPIN(cond, bar) do { unsigned _sp = 0; while (cond) { __builtin_amdgcn_s_sleep(1); \
;     if ((++_sp & 255u) == 0u) { if (xb_ld(&(bar)[XB_TMO])) break; if (_sp > XB_SPIN_CAP) { atomicAdd(&(bar)[XB_TMO], 1u); break; } } } } while (0)
; __device__ __forceinline__ void xcd_barrier(const XcdBarrier& b) {
;     asm volatile("s_waitcnt vmcnt(0)" ::: "memory");
;     __syncthreads();
;     if (threadIdx.x == 0) {
;         unsigned* bar = b.bar;
;         __builtin_amdgcn_s_waitcnt(0);
;         unsigned nloc = b.st[0], nx = b.st[1];
;         if (nloc == 0u) { xcd_barrier_complete(bar, b.x, nloc, nx); b.st[0] = nloc; b.st[1] = nx; }
;         const unsigned old = xb_add(&bar[XB_XSUB(b.x)], 1u);
;         const unsigned gen = old / nloc;
;         if (old + 1u == (gen + 1u) * nloc) {
;             __builtin_amdgcn_fence(__ATOMIC_RELEASE, "agent");
;             asm volatile("s_waitcnt vmcnt(0)" ::: "memory");
;             const unsigned og = xb_add(&bar[XB_TOP], 1u);
;             const unsigned tg = og / nx;
;             if (og + 1u == (tg + 1u) * nx) xb_add(&bar[XB_TOPGEN], 1u);
;             else XB_SPIN(xb_ld(&bar[XB_TOPGEN]) == tg, bar);
;             __builtin_amdgcn_fence(__ATOMIC_ACQUIRE, "agent");
;             xb_add(&bar[XB_XGEN(b.x)], 1u);
;             asm volatile("s_waitcnt vmcnt(0)" ::: "memory");
;         } else {
;             XB_SPIN(xb_ld(&bar[XB_XGEN(b.x)]) == gen, bar);
;             __builtin_amdgcn_fence(__ATOMIC_ACQUIRE, "agent");
;             asm volatile("s_waitcnt vmcnt(0)" ::: "memory");
;         }
;     }
;     __syncthreads();
; }
.LBB0_536:
	s_or_b64 exec, exec, s[0:1]
	v_readfirstlane_b32 s101, v169
	s_nop 3
	s_lshr_b32 s101, s101, 6
	s_cmp_eq_u32 s101, 0
	s_cbranch_scc1 .Lcv_skip_C
	v_readlane_b32 s100, v255, 44
	s_nop 3
	s_cmp_gt_u32 s100, 2
	s_cbranch_scc1 .Lcv_skip_C
	s_add_i32 s100, s100, 1
	s_mul_i32 s98, s100, 0x3000
	s_add_i32 s100, s98, 4916
	s_add_i32 s99, s100, 2458
	s_add_i32 s98, s98, 0x3000
	s_min_i32 s99, s99, s98
	s_sub_i32 s100, s100, 1
	s_mov_b32 s98, 7
	s_mov_b32 s101, 3
	v_readfirstlane_b32 s3, v169
	s_branch .Lcv_entry

; __device__ __forceinline__ unsigned xb_ld(unsigned* p)              { return __hip_atomic_load(p, __ATOMIC_RELAXED, __HIP_MEMORY_SCOPE_AGENT); }
; __device__ __forceinline__ unsigned xb_add(unsigned* p, unsigned v) { return __hip_atomic_fetch_add(p, v, __ATOMIC_RELAXED, __HIP_MEMORY_SCOPE_AGENT); }
; #define XB_SPIN(cond, bar) do { unsigned _sp = 0; while (cond) { __builtin_amdgcn_s_sleep(1); \
;     if ((++_sp & 255u) == 0u) { if (xb_ld(&(bar)[XB_TMO])) break; if (_sp > XB_SPIN_CAP) { atomicAdd(&(bar)[XB_TMO], 1u); break; } } } } while (0)
; __device__ __forceinline__ void xcd_barrier(const XcdBarrier& b) {
;     asm volatile("s_waitcnt vmcnt(0)" ::: "memory");
;     __syncthreads();
;     if (threadIdx.x == 0) {
;         unsigned* bar = b.bar;
;         __builtin_amdgcn_s_waitcnt(0);
;         unsigned nloc = b.st[0], nx = b.st[1];
;         if (nloc == 0u) { xcd_barrier_complete(bar, b.x, nloc, nx); b.st[0] = nloc; b.st[1] = nx; }
;         const unsigned old = xb_add(&bar[XB_XSUB(b.x)], 1u);
;         const unsigned gen = old / nloc;
;         if (old + 1u == (gen + 1u) * nloc) {
;             __builtin_amdgcn_fence(__ATOMIC_RELEASE, "agent");
;             asm volatile("s_waitcnt vmcnt(0)" ::: "memory");
;             const unsigned og = xb_add(&bar[XB_TOP], 1u);
;             const unsigned tg = og / nx;
;             if (og + 1u == (tg + 1u) * nx) xb_add(&bar[XB_TOPGEN], 1u);
;             else XB_SPIN(xb_ld(&bar[XB_TOPGEN]) == tg, bar);
;             __builtin_amdgcn_fence(__ATOMIC_ACQUIRE, "agent");
;             xb_add(&bar[XB_XGEN(b.x)], 1u);
;             asm volatile("s_waitcnt vmcnt(0)" ::: "memory");
;         } else {
;             XB_SPIN(xb_ld(&bar[XB_XGEN(b.x)]) == gen, bar);
;             __builtin_amdgcn_fence(__ATOMIC_ACQUIRE, "agent");
;             asm volatile("s_waitcnt vmcnt(0)" ::: "memory");
;         }
;     }
;     __syncthreads();
; }
.LBB0_615:
	s_or_b64 exec, exec, s[0:1]
	v_readfirstlane_b32 s101, v169
	s_nop 3
	s_lshr_b32 s101, s101, 6
	s_cmp_eq_u32 s101, 0
	s_cbranch_scc1 .Lcv_skip_D
	v_readlane_b32 s100, v255, 44
	s_nop 3
	s_cmp_gt_u32 s100, 2
	s_cbranch_scc1 .Lcv_skip_D
	s_add_i32 s100, s100, 1
	s_mul_i32 s98, s100, 0x3000
	s_add_i32 s100, s98, 7374
	s_add_i32 s99, s100, 2458
	s_add_i32 s98, s98, 0x3000
	s_min_i32 s99, s99, s98
	s_sub_i32 s100, s100, 1
	s_mov_b32 s98, 7
	s_mov_b32 s101, 4
	v_readfirstlane_b32 s3, v169
	s_branch .Lcv_entry

; #define LAS __attribute__((address_space(3)))
; __device__ __forceinline__ unsigned xb_add(unsigned* p, unsigned v) { return __hip_atomic_fetch_add(p, v, __ATOMIC_RELAXED, __HIP_MEMORY_SCOPE_AGENT); }
; __device__ __forceinline__ unsigned xb_xcc_id() { return (unsigned)__builtin_amdgcn_s_getreg((3 << 11) | 20) & 0xFu; }
; __device__ __forceinline__ XcdBarrier xcd_barrier_post(unsigned* bar, volatile LAS unsigned* st) {
;     XcdBarrier b; b.bar = bar; b.x = xb_xcc_id(); b.st = st;
;     if (threadIdx.x == 0) (void)xb_add(&bar[XB_XCNT(b.x)], 1u);
;     return b;
; }
; __global__ void __launch_bounds__(NWAVES * 64, 2) hybrid_fwd(Args args) {
;     ...
;     for (int l = 0; l < DEPTH; ++l) {
;         const int p0 = 1 + 5 * l;
;         for (int rep = 0; rep < ((DUP & 2) ? 2 : 1); ++rep)
;         if (IN(p0) && !NO_PROJ) {
;             int ll = l, z = 0; asm volatile("" : "+s"(ll), "+s"(z));
;             unsigned char* w = (unsigned char*)args.in[z + 17]; float* xout = (float*)args.in[z + 16];
;             pg8::Gemm g{(const bf16*)(w + WS_XB), (const bf16*)(w + WS_WIN) + (size_t)ll * PW * D, T, PW, D, 1  }; pg8::StaticOrder S; S.init(T, PW, G, bx);
;             pg8::EpiProj E{(bf16*)(w + WS_PROJ), (const float*)(w + WS_SSQ) + (size_t)(2 * ll) * T * 32, args.in[z + 4] + ll * 64, args.in[z + 5] + ll * 64, PW};
;             pg8::gemm_phase<pg8::EpiProj, pg8::StaticOrder, true, true>((LAS unsigned char*)lds, g, S, E);
.Lcv_restore:
	s_getreg_b32 s0, hwreg(HW_REG_XCC_ID, 0, 4)
	s_and_b32 s2, s0, 15
	s_cmpk_lt_i32 s80, 0x300
	s_cselect_b64 s[4:5], -1, 0
	v_writelane_b32 v254, s4, 7
	s_ashr_i32 s1, s80, 31
	s_load_dwordx2 s[6:7], s[84:85], 0x88
	v_writelane_b32 v254, s5, 8
	v_writelane_b32 v254, s1, 9
	s_lshr_b32 s1, s1, 29
	s_add_i32 s1, s80, s1
	s_ashr_i32 s3, s1, 3
	s_and_b32 s1, s1, -8
	s_sub_i32 s1, s80, s1
	s_ashr_i32 s4, s88, 31
	v_writelane_b32 v254, s4, 10
	s_waitcnt lgkmcnt(0)
	s_add_u32 s4, s6, 0x200
	s_addc_u32 s5, s7, 0
	v_writelane_b32 v254, s4, 11
	s_mul_i32 s0, s89, s88
	v_mbcnt_lo_u32_b32 v0, -1, 0
	v_writelane_b32 v254, s5, 12
	s_add_u32 s4, s6, 0x1000
	s_addc_u32 s5, s7, 0
	v_writelane_b32 v254, s4, 13
	v_mbcnt_hi_u32_b32 v190, -1, v0
	v_and_b32_e32 v0, 64, v190
	v_writelane_b32 v254, s5, 14
	s_add_u32 s4, s6, 0x1100
	s_addc_u32 s5, s7, 0
	v_writelane_b32 v254, s4, 15
	s_movk_i32 s33, 0x300
	v_or_b32_e32 v189, 0x200, v177
	v_writelane_b32 v254, s5, 16
	s_add_u32 s4, s6, 0x1200
	s_addc_u32 s5, s7, 0
	v_writelane_b32 v254, s4, 17
	v_or_b32_e32 v183, 0x240, v177
	s_movk_i32 s64, 0x60
	v_writelane_b32 v254, s5, 18
	s_add_u32 s4, s6, 0x1300
	s_addc_u32 s5, s7, 0
	v_writelane_b32 v254, s4, 19
	s_cmp_eq_u32 s2, 15
	v_mov_b32_e32 v145, 0
	v_writelane_b32 v254, s5, 20
	s_cselect_b64 s[4:5], -1, 0
	v_writelane_b32 v254, s4, 21
	s_cmp_eq_u32 s2, 14
	v_mov_b32_e32 v186, 0x358637bd
	v_writelane_b32 v254, s5, 22
	s_cselect_b64 s[4:5], -1, 0
	v_writelane_b32 v254, s4, 23
	s_cmp_eq_u32 s2, 13
	v_mov_b32_e32 v187, 0x260
	v_writelane_b32 v254, s5, 24
	s_cselect_b64 s[4:5], -1, 0
	v_writelane_b32 v254, s4, 25
	s_cmp_eq_u32 s2, 12
	v_mov_b32_e32 v188, 1
	v_writelane_b32 v254, s5, 26
	s_cselect_b64 s[4:5], -1, 0
	v_writelane_b32 v254, s4, 27
	s_cmp_eq_u32 s2, 11
	v_xor_b32_e32 v191, 16, v190
	v_writelane_b32 v254, s5, 28
	s_cselect_b64 s[4:5], -1, 0
	v_writelane_b32 v254, s4, 29
	s_cmp_eq_u32 s2, 10
	v_add_u32_e32 v192, 64, v0
	v_writelane_b32 v254, s5, 30
	s_cselect_b64 s[4:5], -1, 0
	v_writelane_b32 v254, s4, 31
	s_cmp_eq_u32 s2, 9
	v_xor_b32_e32 v193, 32, v190
	v_writelane_b32 v254, s5, 32
	s_cselect_b64 s[4:5], -1, 0
	v_writelane_b32 v254, s4, 33
	s_cmp_eq_u32 s2, 8
	v_mov_b32_e32 v194, 31
	v_writelane_b32 v254, s5, 34
	s_cselect_b64 s[4:5], -1, 0
	v_writelane_b32 v254, s4, 35
	s_cmp_eq_u32 s2, 7
	v_mov_b64_e32 v[146:147], 0x300
	v_writelane_b32 v254, s5, 36
	s_cselect_b64 s[4:5], -1, 0
	v_writelane_b32 v254, s4, 37
	s_cmp_eq_u32 s2, 6
	v_mov_b64_e32 v[148:149], 0x2ff
	v_writelane_b32 v254, s5, 38
	s_cselect_b64 s[4:5], -1, 0
	v_writelane_b32 v254, s4, 39
	s_cmp_eq_u32 s2, 5
	v_mov_b32_e32 v195, 0x7f800000
	v_writelane_b32 v254, s5, 40
	s_cselect_b64 s[4:5], -1, 0
	v_writelane_b32 v254, s4, 41
	s_cmp_eq_u32 s2, 4
	v_mov_b32_e32 v196, 0x3000
	v_writelane_b32 v254, s5, 42
	s_cselect_b64 s[4:5], -1, 0
	v_writelane_b32 v254, s4, 43
	s_cmp_eq_u32 s2, 3
	v_mov_b64_e32 v[150:151], 0x1a380800
	v_writelane_b32 v254, s5, 44
	s_cselect_b64 s[4:5], -1, 0
	v_writelane_b32 v254, s4, 45
	s_cmp_eq_u32 s2, 2
	v_mov_b64_e32 v[152:153], 0xff
	v_writelane_b32 v254, s5, 46
	s_cselect_b64 s[4:5], -1, 0
	v_writelane_b32 v254, s4, 47
	s_cmp_eq_u32 s2, 1
	v_mov_b64_e32 v[154:155], 0x100
	v_writelane_b32 v254, s5, 48
	s_cselect_b64 s[4:5], -1, 0
	v_writelane_b32 v254, s4, 49
	s_cmp_eq_u32 s2, 0
	v_mov_b64_e32 v[156:157], 0x400
	v_writelane_b32 v254, s5, 50
	s_cselect_b64 s[4:5], -1, 0
	s_lshl_b32 s2, s2, 8
	v_writelane_b32 v254, s4, 51
	s_add_u32 s2, s6, s2
	v_mov_b64_e32 v[158:159], 0x3ff
	v_writelane_b32 v254, s5, 52
	s_addc_u32 s4, s7, 0
	s_add_u32 s8, s2, 0x1400
	s_addc_u32 s9, s4, 0
	v_writelane_b32 v254, s8, 53
	s_mov_b32 s65, 0xf800000
	s_movk_i32 s58, 0x2000
	v_writelane_b32 v254, s9, 54
	s_add_u32 s8, s2, 0x2400
	s_addc_u32 s9, s4, 0
	v_writelane_b32 v254, s8, 55
	s_add_u32 s4, s6, 0x3400
	s_addc_u32 s5, s7, 0
	v_writelane_b32 v254, s9, 56
	v_writelane_b32 v254, s4, 57
	s_movk_i32 s70, 0x3000
	s_movk_i32 s72, 0xff
	v_writelane_b32 v254, s5, 58
	s_add_u32 s4, s6, 0x3500
	s_addc_u32 s5, s7, 0
	v_writelane_b32 v254, s4, 59
	s_movk_i32 s6, 0x61
	s_movk_i32 s35, 0x1800
	v_writelane_b32 v254, s5, 60
	s_mov_b32 s26, 0
	v_readlane_b32 s2, v254, 0
	s_cmpk_lt_i32 s2, 0x100
	s_cselect_b64 s[4:5], -1, 0
	v_writelane_b32 v254, s4, 61
	s_cmpk_lt_i32 s80, 0x100
	s_mov_b64 s[36:37], 0x800
	v_writelane_b32 v254, s5, 62
	s_cselect_b64 s[4:5], -1, 0
	s_lshl_b32 s2, s1, 5
	v_writelane_b32 v254, s4, 63
	s_cmpk_lt_i32 s80, 0x400
	s_mov_b64 s[94:95], 0x80
	v_writelane_b32 v255, s5, 0
	s_cselect_b64 s[4:5], -1, 0
	v_writelane_b32 v255, s4, 1
	s_mov_b64 s[74:75], 0x1a381080
	s_mov_b64 s[82:83], 0x1800
	v_writelane_b32 v255, s5, 2
	s_load_dword s5, s[84:85], 0xa0
	s_lshl_b32 s4, s1, 7
	s_cmp_lt_i32 s1, 0
	s_cselect_b32 s6, s6, 0x60
	s_mov_b64 s[86:87], 0x2800
	s_waitcnt lgkmcnt(0)
; #define LAS __attribute__((address_space(3)))
; #define SEAM(k) do { } while (0)
; #define SEAM(k) do { if ((k) + 1 < hi) { if ((k) == 0) grid.sync(); else xcd_barrier(xbar); if (DUP & 16) { xcd_barrier(xbar); xcd_barrier(xbar); } } } while (0)
; __global__ void __launch_bounds__(NWAVES * 64, 2) hybrid_fwd(Args args) {
;     ...
;     for (int l = 0; l < DEPTH; ++l) {
;         const int p0 = 1 + 5 * l;
;         for (int rep = 0; rep < ((DUP & 2) ? 2 : 1); ++rep)
;         if (IN(p0) && !NO_PROJ) {
;             int ll = l, z = 0; asm volatile("" : "+s"(ll), "+s"(z));
;             unsigned char* w = (unsigned char*)args.in[z + 17]; float* xout = (float*)args.in[z + 16];
;             pg8::Gemm g{(const bf16*)(w + WS_XB), (const bf16*)(w + WS_WIN) + (size_t)ll * PW * D, T, PW, D, 1  }; pg8::StaticOrder S; S.init(T, PW, G, bx);
;             pg8::EpiProj E{(bf16*)(w + WS_PROJ), (const float*)(w + WS_SSQ) + (size_t)(2 * ll) * T * 32, args.in[z + 4] + ll * 64, args.in[z + 5] + ll * 64, PW};
;             pg8::gemm_phase<pg8::EpiProj, pg8::StaticOrder, true, true>((LAS unsigned char*)lds, g, S, E);
;             SEAM(p0);
;         }
;         for (int rep = 0; rep < ((DUP & 4) ? 2 : 1); ++rep)
;         if (IN(p0 + 1) && !NO_ATT) {
;             int ll = l, z = 0; asm volatile("" : "+s"(ll), "+s"(z));
;             unsigned char* w = (unsigned char*)args.in[z + 17]; float* xout = (float*)args.in[z + 16];
;             const bf16* PROJ = (const bf16*)(w + WS_PROJ); bf16* MIX = (bf16*)(w + WS_MIX); const float* BT = (const float*)(w + WS_BT);
;             const float lam_init = 0.8f - 0.6f * expf(-0.3f * (float)ll);
;             float a = args.in[z + 6][ll * 64 + lane] * args.in[z + 7][ll * 64 + lane], b2 = args.in[z + 8][ll * 64 + lane] * args.in[z + 9][ll * 64 + lane];
;             a = wave_sum(a); b2 = wave_sum(b2);
;             const float lam = expf(a) - expf(b2) + lam_init;
;             float gqm = fabsf(args.in[z + 4][ll * 64 + lane]), gkm = fabsf(args.in[z + 5][ll * 64 + lane]);
; #pragma unroll
;             for (int o = 1; o < 64; o <<= 1) { gqm = fmaxf(gqm, __shfl_xor(gqm, o)); gkm = fmaxf(gkm, __shfl_xor(gkm, o)); }
;             const float gqk = gqm * gkm;
	s_mul_i32 s0, s0, s5
	v_writelane_b32 v255, s0, 3
	s_mul_i32 s0, s1, 33
	s_mul_i32 s5, s1, 0x81
	s_mul_i32 s1, s1, s6
	s_cselect_b32 s2, s0, s2
	s_cselect_b32 s4, s5, s4
	s_add_i32 s1, s1, s3
	s_mul_hi_i32 s0, s1, 0x2aaaaaab
	s_lshr_b32 s5, s0, 31
	s_ashr_i32 s0, s0, 4
	s_add_i32 s0, s0, s5
	s_mul_i32 s5, s0, 0x60
	s_sub_i32 s1, s1, s5
	s_lshl_b32 s6, s0, 2
	s_bfe_i32 s0, s1, 0x80000
	s_bfe_u32 s0, s0, 0x2000d
	s_add_i32 s5, s1, s0
	s_bfe_i32 s0, s5, 0x80000
	s_and_b32 s5, s5, 0xfc
	s_sub_i32 s1, s1, s5
	s_sext_i32_i16 s7, s0
	s_sext_i32_i8 s1, s1
	s_add_i32 s8, s6, s1
	s_ashr_i32 s1, s7, 2
	v_writelane_b32 v255, s1, 4
	s_add_i32 s1, s2, s3
	s_ashr_i32 s2, s1, 31
	s_lshr_b32 s2, s2, 27
	s_add_i32 s2, s1, s2
	s_ashr_i32 s5, s2, 5
	s_and_b32 s2, s2, 0xffe0
	s_sub_i32 s1, s1, s2
	s_bfe_i32 s2, s1, 0x80000
	s_bfe_u32 s2, s2, 0x2000d
	s_add_i32 s6, s1, s2
	s_bfe_i32 s2, s6, 0x80000
	s_and_b32 s6, s6, 0xfc
	s_sub_i32 s1, s1, s6
	s_lshl_b32 s5, s5, 2
	s_sext_i32_i8 s1, s1
	s_add_i32 s10, s5, s1
	s_add_i32 s1, s4, s3
	s_ashr_i32 s3, s1, 31
	s_lshr_b32 s3, s3, 25
	s_add_i32 s3, s1, s3
	s_ashr_i32 s4, s3, 7
	s_and_b32 s3, s3, 0xff80
	s_sub_i32 s1, s1, s3
	s_bfe_i32 s3, s1, 0x80000
	s_bfe_u32 s3, s3, 0x2000d
	s_add_i32 s3, s1, s3
	s_lshl_b32 s5, s4, 2
	s_bfe_i32 s4, s3, 0x80000
	s_and_b32 s3, s3, 0xfc
	s_sub_i32 s1, s1, s3
	s_lshr_b32 s0, s7, 2
	s_sext_i32_i16 s7, s2
	s_sext_i32_i16 s6, s4
	s_sext_i32_i8 s1, s1
	s_lshr_b32 s2, s7, 2
	s_ashr_i32 s7, s7, 2
	s_lshr_b32 s4, s6, 2
	s_add_i32 s12, s5, s1
	s_ashr_i32 s1, s6, 2
	s_cmp_lg_u32 s12, -1
	v_writelane_b32 v255, s1, 5
	s_cselect_b64 s[14:15], -1, 0
	v_writelane_b32 v255, s14, 6
	s_lshl_b32 s1, s12, 8
	s_mov_b32 s6, s12
	v_writelane_b32 v255, s15, 7
	v_writelane_b32 v255, s1, 8
	s_ashr_i32 s13, s12, 31
	v_writelane_b32 v255, s6, 9
	s_lshl_b64 s[12:13], s[12:13], 20
	s_bfe_i64 s[4:5], s[4:5], 0x100000
	v_writelane_b32 v255, s7, 10
	v_writelane_b32 v255, s12, 11
	s_lshl_b64 s[4:5], s[4:5], 20
	s_cmp_lg_u32 s8, -1
	v_writelane_b32 v255, s13, 12
	v_writelane_b32 v255, s4, 13
	s_mov_b64 s[12:13], 0x1000
	s_mov_b32 s15, 0
	v_writelane_b32 v255, s5, 14
	s_cselect_b64 s[4:5], -1, 0
	v_writelane_b32 v255, s4, 15
	s_lshl_b32 s1, s8, 8
	s_ashr_i32 s9, s8, 31
	v_writelane_b32 v255, s5, 16
	v_writelane_b32 v255, s1, 17
	s_bfe_i64 s[0:1], s[0:1], 0x100000
	s_lshl_b64 s[0:1], s[0:1], 20
	v_writelane_b32 v255, s0, 18
	s_ashr_i32 s11, s10, 31
	s_add_i32 s57, 0, 0x19000
	v_writelane_b32 v255, s1, 19
	s_lshl_b32 s0, s10, 8
	v_writelane_b32 v255, s0, 20
	v_writelane_b32 v255, s7, 21
	s_lshl_b32 s0, s7, 8
	v_writelane_b32 v255, s0, 22
	s_bfe_i64 s[0:1], s[2:3], 0x100000
	s_lshl_b64 s[2:3], s[0:1], 20
	v_writelane_b32 v255, s2, 23
	s_lshl_b64 s[0:1], s[0:1], 22
	s_mov_b64 s[4:5], 0x1a381000
	v_writelane_b32 v255, s3, 24
	v_writelane_b32 v255, s0, 25
	s_add_i32 s2, 0, 0x18800
	s_nop 0
	v_writelane_b32 v255, s1, 26
	s_add_i32 s0, 0, 0x23fc0
	v_writelane_b32 v255, s0, 27
	s_add_i32 s0, 0, 0x23fc4
	v_writelane_b32 v255, s0, 28
	s_mov_b32 s0, s8
	v_writelane_b32 v255, s0, 29
	s_nop 1
	v_writelane_b32 v255, s1, 30
	s_lshl_b64 s[0:1], s[8:9], 20
	v_writelane_b32 v255, s0, 31
	s_nop 1
	v_writelane_b32 v255, s1, 32
	s_lshl_b64 s[0:1], s[10:11], 20
	v_writelane_b32 v255, s0, 33
	s_nop 1
	v_writelane_b32 v255, s1, 34
	s_mov_b32 s0, s10
	v_writelane_b32 v255, s0, 35
	s_nop 1
	v_writelane_b32 v255, s1, 36
	s_lshl_b64 s[0:1], s[10:11], 22
	v_writelane_b32 v255, s0, 37
	s_nop 1
	v_writelane_b32 v255, s1, 38
	v_writelane_b32 v255, s80, 39
	v_writelane_b32 v255, s84, 40
	s_nop 1
	v_writelane_b32 v255, s85, 41
	v_writelane_b32 v255, s88, 42
	s_nop 1
	v_writelane_b32 v255, s89, 43
	v_readlane_b32 s26, v255, 44
	v_readlane_b32 s27, v255, 45
	s_nop 3
	s_cmp_eq_u32 s101, 1
	s_cbranch_scc1 .Lcv_fix_A
	s_cmp_eq_u32 s101, 2
	s_cbranch_scc1 .Lcv_fix_B
	s_cmp_eq_u32 s101, 3
	s_cbranch_scc1 .Lcv_fix_C
	s_cmp_eq_u32 s101, 4
	s_cbranch_scc1 .Lcv_fix_D
	s_cmp_eq_u32 s101, 5
	s_cbranch_scc1 .Lcv_fix_E
	s_endpgm
.Lcv_fix_A:
	s_add_i32 s3, s27, 2
	s_mov_b64 s[10:11], -1
	s_mov_b32 s101, 0
	s_nop 3
	s_branch .Lcv_ret_A
.Lcv_fix_B:
	v_readlane_b32 s24, v255, 46
	s_mov_b64 s[78:79], -1
	s_mov_b32 s101, 0
	s_nop 3
	s_branch .Lcv_ret_B
.Lcv_fix_C:
	s_add_i32 s3, s27, 4
	s_mov_b32 s101, 0
	s_nop 3
	s_branch .Lcv_ret_C
.Lcv_fix_D:
	s_add_i32 s3, s27, 5
	s_mov_b64 s[10:11], -1
	s_mov_b32 s101, 0
	s_nop 3
	s_branch .Lcv_ret_D
.Lcv_fix_E:
	s_mov_b32 s101, 0
	s_nop 3
	s_branch .Lcv_ret_E

; __global__ void __launch_bounds__(NWAVES * 64, 2) hybrid_fwd(Args args) {
;     extern __shared__ __attribute__((aligned(16))) unsigned char lds[];
	.amdhsa_kernel _Z10hybrid_fwd4Args
		.amdhsa_group_segment_fixed_size 0
		.amdhsa_private_segment_fixed_size 0
		.amdhsa_kernarg_size 408
		.amdhsa_user_sgpr_count 2
		.amdhsa_user_sgpr_dispatch_ptr 0
		.amdhsa_user_sgpr_queue_ptr 0
		.amdhsa_user_sgpr_kernarg_segment_ptr 1
		.amdhsa_user_sgpr_dispatch_id 0
		.amdhsa_user_sgpr_kernarg_preload_length 0
		.amdhsa_user_sgpr_kernarg_preload_offset 0
		.amdhsa_user_sgpr_private_segment_size 0
		.amdhsa_uses_dynamic_stack 0
		.amdhsa_enable_private_segment 0
		.amdhsa_system_sgpr_workgroup_id_x 1
		.amdhsa_system_sgpr_workgroup_id_y 0
		.amdhsa_system_sgpr_workgroup_id_z 0
		.amdhsa_system_sgpr_workgroup_info 0
		.amdhsa_system_vgpr_workitem_id 2
		.amdhsa_next_free_vgpr 256
		.amdhsa_next_free_sgpr 102
		.amdhsa_accum_offset 256
		.amdhsa_reserve_vcc 1
		.amdhsa_float_round_mode_32 0
		.amdhsa_float_round_mode_16_64 0
		.amdhsa_float_denorm_mode_32 3
		.amdhsa_float_denorm_mode_16_64 3
		.amdhsa_dx10_clamp 1
		.amdhsa_ieee_mode 1
		.amdhsa_fp16_overflow 0
		.amdhsa_tg_split 0
		.amdhsa_exception_fp_ieee_invalid_op 0
		.amdhsa_exception_fp_denorm_src 0
		.amdhsa_exception_fp_ieee_div_zero 0
		.amdhsa_exception_fp_ieee_overflow 0
		.amdhsa_exception_fp_ieee_underflow 0
		.amdhsa_exception_fp_ieee_inexact 0
		.amdhsa_exception_int_div_zero 0
	.end_amdhsa_kernel

; __global__ void __launch_bounds__(NWAVES * 64, 2) hybrid_fwd(Args args) {
;     extern __shared__ __attribute__((aligned(16))) unsigned char lds[];
amdhsa.kernels:
  - .agpr_count:     0
    .args:
      - .offset:         0
        .size:           152
        .value_kind:     by_value
      - .offset:         152
        .size:           4
        .value_kind:     hidden_block_count_x
      - .offset:         156
        .size:           4
        .value_kind:     hidden_block_count_y
      - .offset:         160
        .size:           4
        .value_kind:     hidden_block_count_z
      - .offset:         164
        .size:           2
        .value_kind:     hidden_group_size_x
      - .offset:         166
        .size:           2
        .value_kind:     hidden_group_size_y
      - .offset:         168
        .size:           2
        .value_kind:     hidden_group_size_z
      - .offset:         170
        .size:           2
        .value_kind:     hidden_remainder_x
      - .offset:         172
        .size:           2
        .value_kind:     hidden_remainder_y
      - .offset:         174
        .size:           2
        .value_kind:     hidden_remainder_z
      - .offset:         192
        .size:           8
        .value_kind:     hidden_global_offset_x
      - .offset:         200
        .size:           8
        .value_kind:     hidden_global_offset_y
      - .offset:         208
        .size:           8
        .value_kind:     hidden_global_offset_z
      - .offset:         216
        .size:           2
        .value_kind:     hidden_grid_dims
      - .offset:         240
        .size:           8
        .value_kind:     hidden_multigrid_sync_arg
      - .offset:         272
        .size:           4
        .value_kind:     hidden_dynamic_lds_size
    .group_segment_fixed_size: 0
    .kernarg_segment_align: 8
    .kernarg_segment_size: 408
    .language:       OpenCL C
    .language_version:
      - 2
      - 0
    .max_flat_workgroup_size: 512
    .name:           _Z10hybrid_fwd4Args
    .private_segment_fixed_size: 0
    .sgpr_count:     108
    .sgpr_spill_count: 114
    .symbol:         _Z10hybrid_fwd4Args.kd
    .uniform_work_group_size: 1
    .uses_dynamic_stack: false
    .vgpr_count:     256
    .vgpr_spill_count: 0
    .wavefront_size: 64
